# passCpf: SSD pass C head loop prefetches the next head's XC/ST/D loads one head ahead (into v132-148)
# speedup vs baseline: 1.0002x; 1.0002x over previous
.LBB0_649:
	v_mov_b64_e32 v[4:5], s[94:95]
	v_and_b32_e32 v6, 0x78, v2
	v_mad_i64_i32 v[4:5], vcc, v0, s72, v[4:5]
	v_lshlrev_b32_e32 v64, 1, v6
	v_lshl_add_u64 v[8:9], v[4:5], 0, v[64:65]
	global_load_dwordx4 v[4:7], v[8:9], off offset:2560
	v_add_u32_e32 v3, 0x200, v3
	s_movk_i32 s84, 0x5ff
	v_cmp_lt_u32_e32 vcc, s84, v3
	v_add_u32_e32 v2, 0x1000, v2
	v_add_u32_e32 v0, 32, v0
	s_or_b64 s[0:1], vcc, s[0:1]
	s_waitcnt vmcnt(0)
	ds_write_b128 v1, v[4:7]
	global_load_dwordx4 v[4:7], v[8:9], off offset:2048
	s_waitcnt vmcnt(0)
	ds_write_b128 v1, v[4:7] offset:34816
	v_add_u32_e32 v1, 0x2200, v1
	s_andn2_b64 exec, exec, s[0:1]
	s_cbranch_execnz .LBB0_649
	s_or_b64 exec, exec, s[0:1]
	s_waitcnt lgkmcnt(0)
	s_barrier
	ds_read_b128 v[0:3], v91 offset:8192
	ds_read_b128 v[4:7], v115 offset:43008
	ds_read_b128 v[8:11], v115 offset:47360
	ds_read_b128 v[12:15], v115 offset:51712
	ds_read_b128 v[16:19], v115 offset:56064
	ds_read_b128 v[20:23], v115 offset:60416
	ds_read_b128 v[24:27], v115 offset:64768
	ds_read_b128 v[28:31], v116 offset:43008
	ds_read_b128 v[32:35], v117 offset:43008
	s_waitcnt lgkmcnt(7)
	v_mfma_f32_16x16x32_bf16 v[4:7], v[0:3], v[4:7], 0
	s_and_b32 s78, s78, 31
	s_lshl_b32 s78, s78, 7
	s_or_b32 s94, s78, s86
	s_waitcnt lgkmcnt(6)
	v_mfma_f32_16x16x32_bf16 v[8:11], v[0:3], v[8:11], 0
	v_or_b32_e32 v40, s94, v90
	s_lshl_b32 s78, s92, 10
	s_lshl_b32 s0, s96, 4
	s_waitcnt lgkmcnt(5)
	v_mfma_f32_16x16x32_bf16 v[12:15], v[0:3], v[12:15], 0
	v_readfirstlane_b32 s1, v120
	v_mov_b32_e32 v71, v65
	v_readlane_b32 s80, v234, 9
	s_waitcnt lgkmcnt(4)
	v_mfma_f32_16x16x32_bf16 v[16:19], v[0:3], v[16:19], 0
	s_lshl_b32 s1, s1, 3
	v_readlane_b32 s81, v234, 10
	s_movk_i32 s84, 0x3000
	s_waitcnt lgkmcnt(3)
	v_mfma_f32_16x16x32_bf16 v[20:23], v[0:3], v[20:23], 0
	s_lshl_b32 s68, s92, 3
	s_mov_b32 s96, 0
	v_mov_b32_e32 v121, 0
	s_waitcnt lgkmcnt(2)
	v_mfma_f32_16x16x32_bf16 v[24:27], v[0:3], v[24:27], 0
	s_waitcnt lgkmcnt(1)
	v_mfma_f32_16x16x32_bf16 v[28:31], v[0:3], v[28:31], 0
	s_waitcnt lgkmcnt(0)
	v_mfma_f32_16x16x32_bf16 v[0:3], v[0:3], v[32:35], 0
	ds_read_b128 v[32:35], v91 offset:8256
	ds_read_b128 v[36:39], v115 offset:43072
	s_waitcnt lgkmcnt(0)
	v_mfma_f32_16x16x32_bf16 v[4:7], v[32:35], v[36:39], v[4:7]
	ds_read_b128 v[36:39], v115 offset:47424
	s_waitcnt lgkmcnt(0)
	v_mfma_f32_16x16x32_bf16 v[8:11], v[32:35], v[36:39], v[8:11]
	ds_read_b128 v[36:39], v115 offset:51776
	s_waitcnt lgkmcnt(0)
	v_mfma_f32_16x16x32_bf16 v[12:15], v[32:35], v[36:39], v[12:15]
	ds_read_b128 v[36:39], v115 offset:56128
	s_waitcnt lgkmcnt(0)
	v_mfma_f32_16x16x32_bf16 v[16:19], v[32:35], v[36:39], v[16:19]
	ds_read_b128 v[36:39], v115 offset:60480
	s_waitcnt lgkmcnt(0)
	v_mfma_f32_16x16x32_bf16 v[20:23], v[32:35], v[36:39], v[20:23]
	ds_read_b128 v[36:39], v115 offset:64832
	s_waitcnt lgkmcnt(0)
	v_mfma_f32_16x16x32_bf16 v[24:27], v[32:35], v[36:39], v[24:27]
	ds_read_b128 v[36:39], v116 offset:43072
	s_waitcnt lgkmcnt(0)
	v_mfma_f32_16x16x32_bf16 v[28:31], v[32:35], v[36:39], v[28:31]
	ds_read_b128 v[36:39], v117 offset:43072
	s_waitcnt lgkmcnt(0)
	v_mfma_f32_16x16x32_bf16 v[0:3], v[32:35], v[36:39], v[0:3]
	ds_read_b128 v[32:35], v91 offset:8320
	ds_read_b128 v[36:39], v115 offset:43136
	s_waitcnt lgkmcnt(0)
	v_mfma_f32_16x16x32_bf16 v[4:7], v[32:35], v[36:39], v[4:7]
	ds_read_b128 v[36:39], v115 offset:47488
	s_waitcnt lgkmcnt(0)
	v_mfma_f32_16x16x32_bf16 v[8:11], v[32:35], v[36:39], v[8:11]
	ds_read_b128 v[36:39], v115 offset:51840
	s_waitcnt lgkmcnt(0)
	v_mfma_f32_16x16x32_bf16 v[12:15], v[32:35], v[36:39], v[12:15]
	ds_read_b128 v[36:39], v115 offset:56192
	s_waitcnt lgkmcnt(0)
	v_mfma_f32_16x16x32_bf16 v[16:19], v[32:35], v[36:39], v[16:19]
	ds_read_b128 v[36:39], v115 offset:60544
	s_waitcnt lgkmcnt(0)
	v_mfma_f32_16x16x32_bf16 v[20:23], v[32:35], v[36:39], v[20:23]
	ds_read_b128 v[36:39], v115 offset:64896
	s_waitcnt lgkmcnt(0)
	v_mfma_f32_16x16x32_bf16 v[24:27], v[32:35], v[36:39], v[24:27]
	ds_read_b128 v[36:39], v116 offset:43136
	s_waitcnt lgkmcnt(0)
	v_mfma_f32_16x16x32_bf16 v[28:31], v[32:35], v[36:39], v[28:31]
	ds_read_b128 v[36:39], v117 offset:43136
	s_waitcnt lgkmcnt(0)
	v_mfma_f32_16x16x32_bf16 v[32:35], v[32:35], v[36:39], v[0:3]
	ds_read_b128 v[36:39], v91 offset:8384
	s_nop 1
	ds_read_b128 v[0:3], v115 offset:43200
	s_waitcnt lgkmcnt(0)
	v_mfma_f32_16x16x32_bf16 v[0:3], v[36:39], v[0:3], v[4:7]
	s_nop 2
	ds_read_b128 v[4:7], v115 offset:47552
	s_waitcnt lgkmcnt(0)
	v_mfma_f32_16x16x32_bf16 v[4:7], v[36:39], v[4:7], v[8:11]
	s_nop 2
	ds_read_b128 v[8:11], v115 offset:51904
	s_waitcnt lgkmcnt(0)
	v_mfma_f32_16x16x32_bf16 v[8:11], v[36:39], v[8:11], v[12:15]
	s_nop 2
	ds_read_b128 v[12:15], v115 offset:56256
	s_waitcnt lgkmcnt(0)
	v_mfma_f32_16x16x32_bf16 v[12:15], v[36:39], v[12:15], v[16:19]
	s_nop 2
	ds_read_b128 v[16:19], v115 offset:60608
	s_waitcnt lgkmcnt(0)
	v_mfma_f32_16x16x32_bf16 v[16:19], v[36:39], v[16:19], v[20:23]
	s_nop 2
	ds_read_b128 v[20:23], v115 offset:64960
	s_waitcnt lgkmcnt(0)
	v_mfma_f32_16x16x32_bf16 v[20:23], v[36:39], v[20:23], v[24:27]
	s_nop 2
	ds_read_b128 v[24:27], v116 offset:43200
	s_waitcnt lgkmcnt(0)
	v_mfma_f32_16x16x32_bf16 v[24:27], v[36:39], v[24:27], v[28:31]
	s_nop 2
	ds_read_b128 v[28:31], v117 offset:43200
	s_waitcnt lgkmcnt(0)
	v_mfma_f32_16x16x32_bf16 v[28:31], v[36:39], v[28:31], v[32:35]
	s_nop 2
	v_mov_b64_e32 v[32:33], s[74:75]
	v_mad_i64_i32 v[34:35], vcc, v40, s72, v[32:33]
	v_lshl_add_u64 v[34:35], v[34:35], 0, s[78:79]
	s_lshl_b32 s78, s97, 9
	v_lshl_add_u64 v[72:73], v[34:35], 0, v[70:71]
	v_add_u32_e32 v34, s94, v92
	s_or_b32 s0, s78, s0
	v_mad_i64_i32 v[74:75], s[94:95], v34, s72, v[32:33]
	v_mov_b64_e32 v[32:33], s[80:81]
	s_or_b32 s0, s0, s1
	v_ashrrev_i32_e32 v35, 31, v34
	v_mad_i64_i32 v[76:77], s[94:95], v34, s84, v[32:33]
	v_readlane_b32 s84, v234, 7
	s_ashr_i32 s1, s0, 31
	v_lshlrev_b64 v[32:33], 12, v[34:35]
	v_readlane_b32 s85, v234, 8
	s_lshl_b64 s[0:1], s[0:1], 14
	v_lshl_or_b32 v71, s92, 9, v93
	v_lshl_add_u64 v[78:79], s[84:85], 0, v[32:33]
	v_lshl_add_u64 v[80:81], v[68:69], 0, s[0:1]
	s_barrier
	s_mov_b32 s98, 0
	s_lshl_b32 s100, s98, 7
	s_mov_b32 s101, 0
	v_lshl_add_u64 v[254:255], v[72:73], 0, s[100:101]
	global_load_dwordx4 v[132:135], v[254:255], off offset:16
	global_load_dwordx4 v[136:139], v[254:255], off
	s_sub_i32 s100, s98, s96
	s_lshl_b32 s100, s100, 14
	v_lshl_add_u64 v[254:255], v[80:81], 0, s[100:101]
	global_load_dwordx4 v[140:143], v[254:255], off
	s_add_i32 s100, s100, 0x2000
	v_lshl_add_u64 v[254:255], v[80:81], 0, s[100:101]
	global_load_dwordx4 v[144:147], v[254:255], off
	s_add_i32 s98, s98, s68
	s_lshl_b32 s98, s98, 2
	v_readlane_b32 s100, v235, 23
	v_readlane_b32 s101, v235, 24
	s_nop 3
	s_add_u32 s100, s100, s98
	s_addc_u32 s101, s101, 0
	global_load_dword v148, v65, s[100:101]
	global_load_dword v150, v65, s[100:101]
	global_load_dword v151, v65, s[100:101]
	global_load_dword v152, v65, s[100:101]
	global_load_dword v153, v65, s[100:101]

.LBB0_715:
	s_or_b64 exec, exec, s[0:1]
	s_lshl_b32 s78, s96, 7
	ds_write_b16 v119, v34 offset:44048
	v_lshl_add_u32 v48, s78, 2, v95
	ds_read_b32 v48, v48
	s_lshl_b32 s0, s96, 6
	s_mov_b64 s[94:95], 0
	s_waitcnt vmcnt(8)
	v_lshlrev_b32_e32 v44, 16, v132
	v_and_b32_e32 v32, 0xffff0000, v132
	s_waitcnt lgkmcnt(0)
	v_mul_f32_e32 v32, v48, v32
	s_waitcnt vmcnt(7)
	v_lshlrev_b32_e32 v41, 16, v137
	v_cvt_pk_bf16_f32 v32, v32, s0
	ds_write_b16 v102, v32 offset:2176
	v_mul_f32_e32 v32, v48, v41
	v_lshlrev_b32_e32 v45, 16, v133
	v_cvt_pk_bf16_f32 v32, v32, s0
	ds_write_b16 v100, v32 offset:544
	v_mul_f32_e32 v32, v48, v45
	v_and_b32_e32 v37, 0xffff0000, v137
	v_cvt_pk_bf16_f32 v32, v32, s0
	ds_write_b16 v103, v32 offset:2176
	v_mul_f32_e32 v32, v48, v37
	v_and_b32_e32 v33, 0xffff0000, v133
	v_cvt_pk_bf16_f32 v32, v32, s0
	ds_write_b16 v100, v32 offset:816
	v_mul_f32_e32 v32, v48, v33
	v_lshlrev_b32_e32 v42, 16, v138
	v_cvt_pk_bf16_f32 v32, v32, s0
	ds_write_b16 v104, v32 offset:2176
	v_mul_f32_e32 v32, v48, v42
	v_lshlrev_b32_e32 v46, 16, v134
	v_cvt_pk_bf16_f32 v32, v32, s0
	ds_write_b16 v100, v32 offset:1088
	v_mul_f32_e32 v32, v48, v46
	v_and_b32_e32 v38, 0xffff0000, v138
	v_cvt_pk_bf16_f32 v32, v32, s0
	ds_write_b16 v105, v32 offset:2176
	v_mul_f32_e32 v32, v48, v38
	v_and_b32_e32 v34, 0xffff0000, v134
	v_cvt_pk_bf16_f32 v32, v32, s0
	ds_write_b16 v100, v32 offset:1360
	v_mul_f32_e32 v32, v48, v34
	v_lshlrev_b32_e32 v43, 16, v139
	v_cvt_pk_bf16_f32 v32, v32, s0
	ds_write_b16 v106, v32 offset:2176
	v_mul_f32_e32 v32, v48, v43
	v_lshlrev_b32_e32 v47, 16, v135
	v_cvt_pk_bf16_f32 v32, v32, s0
	ds_write_b16 v100, v32 offset:1632
	v_mul_f32_e32 v32, v48, v47
	v_and_b32_e32 v39, 0xffff0000, v139
	v_cvt_pk_bf16_f32 v32, v32, s0
	v_lshlrev_b32_e32 v40, 16, v136
	ds_write_b16 v107, v32 offset:2176
	v_mul_f32_e32 v32, v48, v39
	v_and_b32_e32 v35, 0xffff0000, v135
	v_mul_f32_e32 v40, v48, v40
	v_cvt_pk_bf16_f32 v32, v32, s0
	v_and_b32_e32 v36, 0xffff0000, v136
	v_cvt_pk_bf16_f32 v40, v40, s0
	ds_write_b16 v100, v32 offset:1904
	v_mul_f32_e32 v32, v48, v35
	ds_write_b16 v100, v40
	v_mul_f32_e32 v40, v48, v44
	v_mul_f32_e32 v36, v48, v36
	v_cvt_pk_bf16_f32 v32, v32, s0
	v_cvt_pk_bf16_f32 v40, v40, s0
	v_cvt_pk_bf16_f32 v36, v36, s0
	ds_write_b16 v108, v32 offset:2176
	ds_write_b16 v101, v40 offset:2176
	ds_write_b16 v100, v36 offset:272
	s_waitcnt vmcnt(4)
	ds_write_b128 v114, v[140:143]
	ds_write_b128 v114, v[144:147] offset:8704
	v_mov_b32_e32 v252, v148
	v_add_lshl_u32 v253, s0, v71, 1
	v_add_co_u32_e32 v254, vcc, v76, v253
	s_nop 1
	v_addc_co_u32_e32 v255, vcc, 0, v77, vcc
	global_load_dwordx2 v[236:237], v[254:255], off
	global_load_dwordx2 v[238:239], v[254:255], off offset:32
	global_load_dwordx2 v[240:241], v[254:255], off offset:64
	global_load_dwordx2 v[242:243], v[254:255], off offset:96
	v_add_co_u32_e32 v254, vcc, v74, v253
	s_nop 1
	v_addc_co_u32_e32 v255, vcc, 0, v75, vcc
	global_load_dwordx2 v[244:245], v[254:255], off
	global_load_dwordx2 v[246:247], v[254:255], off offset:32
	global_load_dwordx2 v[248:249], v[254:255], off offset:64
	global_load_dwordx2 v[250:251], v[254:255], off offset:96
	s_waitcnt lgkmcnt(0)
	s_barrier
	s_add_i32 s98, s96, 1
	s_min_u32 s98, s98, 7
	s_lshl_b32 s100, s98, 7
	s_mov_b32 s101, 0
	v_lshl_add_u64 v[254:255], v[72:73], 0, s[100:101]
	global_load_dwordx4 v[132:135], v[254:255], off offset:16
	global_load_dwordx4 v[136:139], v[254:255], off
	s_sub_i32 s100, s98, s96
	s_lshl_b32 s100, s100, 14
	v_lshl_add_u64 v[254:255], v[80:81], 0, s[100:101]
	global_load_dwordx4 v[140:143], v[254:255], off
	s_add_i32 s100, s100, 0x2000
	v_lshl_add_u64 v[254:255], v[80:81], 0, s[100:101]
	global_load_dwordx4 v[144:147], v[254:255], off
	s_add_i32 s98, s98, s68
	s_lshl_b32 s98, s98, 2
	v_readlane_b32 s100, v235, 23
	v_readlane_b32 s101, v235, 24
	s_nop 3
	s_add_u32 s100, s100, s98
	s_addc_u32 s101, s101, 0
	global_load_dword v148, v65, s[100:101]
	v_lshl_add_u32 v64, s78, 2, v98
	ds_read_b32 v64, v64 offset:4096
	ds_read_b128 v[186:189], v91 offset:43008
	ds_read_b128 v[190:193], v96
	ds_read_b128 v[194:197], v96 offset:4352
	ds_read_b128 v[198:201], v96 offset:8704
	ds_read_b128 v[202:205], v96 offset:13056
	ds_read_b128 v[206:209], v91 offset:43072
	ds_read_b128 v[210:213], v96 offset:64
	ds_read_b128 v[214:217], v96 offset:4416
	ds_read_b128 v[218:221], v96 offset:8768
	ds_read_b128 v[222:225], v96 offset:13120
	s_add_i32 s94, s96, s68
	s_mov_b32 s95, s79
	s_lshl_b64 vcc, s[94:95], 2
	v_readlane_b32 s80, v235, 23
	v_readlane_b32 s94, v235, 37
	v_readlane_b32 s81, v235, 24
	v_readlane_b32 s95, v235, 38
	s_add_u32 s94, s80, vcc_lo
	s_addc_u32 s95, s81, vcc_hi
	s_add_i32 s96, s96, 1
	s_cmp_eq_u32 s96, 8
	v_readlane_b32 s82, v235, 25
	v_readlane_b32 s83, v235, 26
	v_readlane_b32 s84, v235, 27
	v_readlane_b32 s85, v235, 28
	v_readlane_b32 s86, v235, 29
	v_readlane_b32 s87, v235, 30
	v_readlane_b32 s88, v235, 31
	v_readlane_b32 s89, v235, 32
	v_readlane_b32 s90, v235, 33
	v_readlane_b32 s91, v235, 34
	v_readlane_b32 s92, v235, 35
	v_readlane_b32 s93, v235, 36
	s_waitcnt lgkmcnt(5)
	v_mfma_f32_16x16x32_bf16 v[56:59], v[190:193], v[186:189], 0
	v_mfma_f32_16x16x32_bf16 v[48:51], v[194:197], v[186:189], 0
	v_mfma_f32_16x16x32_bf16 v[40:43], v[198:201], v[186:189], 0
	v_mfma_f32_16x16x32_bf16 v[32:35], v[202:205], v[186:189], 0
	ds_read_b128 v[186:189], v91 offset:43136
	ds_read_b128 v[190:193], v96 offset:128
	ds_read_b128 v[194:197], v96 offset:4480
	ds_read_b128 v[198:201], v96 offset:8832
	ds_read_b128 v[202:205], v96 offset:13184
	v_mul_f32_e32 v64, 0x3fb8aa3b, v64
	v_exp_f32_e32 v82, v64
	v_add_lshl_u32 v64, s0, v71, 1
	s_waitcnt lgkmcnt(5)
	v_mfma_f32_16x16x32_bf16 v[56:59], v[210:213], v[206:209], v[56:59]
	v_mfma_f32_16x16x32_bf16 v[48:51], v[214:217], v[206:209], v[48:51]
	v_mfma_f32_16x16x32_bf16 v[40:43], v[218:221], v[206:209], v[40:43]
	v_mfma_f32_16x16x32_bf16 v[32:35], v[222:225], v[206:209], v[32:35]
	ds_read_b128 v[206:209], v91 offset:43200
	ds_read_b128 v[210:213], v96 offset:192
	ds_read_b128 v[214:217], v96 offset:4544
	ds_read_b128 v[218:221], v96 offset:8896
	ds_read_b128 v[222:225], v96 offset:13248
	s_waitcnt lgkmcnt(5)
	v_mfma_f32_16x16x32_bf16 v[56:59], v[190:193], v[186:189], v[56:59]
	v_mfma_f32_16x16x32_bf16 v[48:51], v[194:197], v[186:189], v[48:51]
	v_mfma_f32_16x16x32_bf16 v[40:43], v[198:201], v[186:189], v[40:43]
	v_mfma_f32_16x16x32_bf16 v[32:35], v[202:205], v[186:189], v[32:35]
	ds_read_b128 v[186:189], v91 offset:8192
	ds_read_b128 v[190:193], v97
	ds_read_b128 v[194:197], v97 offset:4352
	ds_read_b128 v[198:201], v97 offset:8704
	ds_read_b128 v[202:205], v97 offset:13056
	s_waitcnt lgkmcnt(5)
	v_mfma_f32_16x16x32_bf16 v[56:59], v[210:213], v[206:209], v[56:59]
	v_mfma_f32_16x16x32_bf16 v[48:51], v[214:217], v[206:209], v[48:51]
	v_mfma_f32_16x16x32_bf16 v[40:43], v[218:221], v[206:209], v[40:43]
	v_mfma_f32_16x16x32_bf16 v[32:35], v[222:225], v[206:209], v[32:35]
	ds_read_b128 v[206:209], v91 offset:8256
	ds_read_b128 v[210:213], v97 offset:64
	ds_read_b128 v[214:217], v97 offset:4416
	ds_read_b128 v[218:221], v97 offset:8768
	ds_read_b128 v[222:225], v97 offset:13120
	s_waitcnt lgkmcnt(5)
	v_mfma_f32_16x16x32_bf16 v[60:63], v[190:193], v[186:189], 0
	v_mfma_f32_16x16x32_bf16 v[52:55], v[194:197], v[186:189], 0
	v_mfma_f32_16x16x32_bf16 v[44:47], v[198:201], v[186:189], 0
	v_mfma_f32_16x16x32_bf16 v[36:39], v[202:205], v[186:189], 0
	ds_read_b128 v[186:189], v91 offset:8320
	ds_read_b128 v[190:193], v97 offset:128
	ds_read_b128 v[194:197], v97 offset:4480
	ds_read_b128 v[198:201], v97 offset:8832
	ds_read_b128 v[202:205], v97 offset:13184
	s_waitcnt lgkmcnt(5)
	v_mfma_f32_16x16x32_bf16 v[60:63], v[210:213], v[206:209], v[60:63]
	v_mfma_f32_16x16x32_bf16 v[52:55], v[214:217], v[206:209], v[52:55]
	v_mfma_f32_16x16x32_bf16 v[44:47], v[218:221], v[206:209], v[44:47]
	v_mfma_f32_16x16x32_bf16 v[36:39], v[222:225], v[206:209], v[36:39]
	ds_read_b128 v[206:209], v91 offset:8384
	ds_read_b128 v[210:213], v97 offset:192
	ds_read_b128 v[214:217], v97 offset:4544
	ds_read_b128 v[218:221], v97 offset:8896
	ds_read_b128 v[222:225], v97 offset:13248
	s_waitcnt lgkmcnt(5)
	v_mfma_f32_16x16x32_bf16 v[60:63], v[190:193], v[186:189], v[60:63]
	v_mfma_f32_16x16x32_bf16 v[52:55], v[194:197], v[186:189], v[52:55]
	v_mfma_f32_16x16x32_bf16 v[44:47], v[198:201], v[186:189], v[44:47]
	v_mfma_f32_16x16x32_bf16 v[36:39], v[202:205], v[186:189], v[36:39]
	s_waitcnt lgkmcnt(0)
	v_mfma_f32_16x16x32_bf16 v[60:63], v[210:213], v[206:209], v[60:63]
	v_mfma_f32_16x16x32_bf16 v[52:55], v[214:217], v[206:209], v[52:55]
	v_mfma_f32_16x16x32_bf16 v[44:47], v[218:221], v[206:209], v[44:47]
	v_mfma_f32_16x16x32_bf16 v[36:39], v[222:225], v[206:209], v[36:39]
	s_nop 7
	s_nop 1
	v_pk_fma_f32 v[56:57], v[60:61], v[82:83], v[56:57] op_sel_hi:[1,0,1]
	v_pk_fma_f32 v[58:59], v[62:63], v[82:83], v[58:59] op_sel_hi:[1,0,1]
	v_pk_fma_f32 v[48:49], v[52:53], v[82:83], v[48:49] op_sel_hi:[1,0,1]
	v_pk_fma_f32 v[50:51], v[54:55], v[82:83], v[50:51] op_sel_hi:[1,0,1]
	v_pk_fma_f32 v[40:41], v[44:45], v[82:83], v[40:41] op_sel_hi:[1,0,1]
	v_pk_fma_f32 v[42:43], v[46:47], v[82:83], v[42:43] op_sel_hi:[1,0,1]
	v_pk_fma_f32 v[32:33], v[36:37], v[82:83], v[32:33] op_sel_hi:[1,0,1]
	v_pk_fma_f32 v[34:35], v[38:39], v[82:83], v[34:35] op_sel_hi:[1,0,1]
	s_mov_b64 s[0:1], 0x4000
	v_lshl_add_u64 v[80:81], v[80:81], 0, s[0:1]
	s_waitcnt vmcnt(12)
	v_lshlrev_b32_e32 v128, 16, v236
	v_and_b32_e32 v129, 0xffff0000, v236
	s_waitcnt vmcnt(8)
	v_lshlrev_b32_e32 v126, 16, v244
	v_and_b32_e32 v127, 0xffff0000, v244
	v_mul_f32_e32 v122, 0xbfb8aa3b, v128
	v_mul_f32_e32 v60, 0xbfb8aa3b, v129
	v_exp_f32_e32 v122, v122
	v_exp_f32_e32 v60, v60
	v_pk_fma_f32 v[56:57], v[252:253], v[126:127], v[56:57] op_sel_hi:[0,1,1]
	v_add_f32_e32 v122, 1.0, v122
	v_add_f32_e32 v60, 1.0, v60
	v_rcp_f32_e32 v130, v122
	v_rcp_f32_e32 v131, v60
	v_lshlrev_b32_e32 v122, 16, v237
	v_pk_mul_f32 v[60:61], v[130:131], v[128:129]
	s_nop 0
	v_pk_mul_f32 v[56:57], v[56:57], v[60:61]
	s_nop 0
	v_pk_mul_f32 v[60:61], v[56:57], v[56:57]
	s_nop 0
	v_add_f32_e32 v60, v121, v60
	v_add_f32_e32 v61, v61, v60
	v_cvt_pk_bf16_f32 v60, v56, v57
	v_lshlrev_b32_e32 v56, 16, v245
	v_and_b32_e32 v57, 0xffff0000, v245
	v_and_b32_e32 v123, 0xffff0000, v237
	v_mul_f32_e32 v121, 0xbfb8aa3b, v122
	v_pk_fma_f32 v[56:57], v[252:253], v[56:57], v[58:59] op_sel_hi:[0,1,1]
	v_mul_f32_e32 v58, 0xbfb8aa3b, v123
	v_exp_f32_e32 v121, v121
	v_exp_f32_e32 v58, v58
	v_add_f32_e32 v121, 1.0, v121
	v_add_f32_e32 v58, 1.0, v58
	v_rcp_f32_e32 v124, v121
	v_rcp_f32_e32 v125, v58
	s_nop 0
	v_pk_mul_f32 v[58:59], v[124:125], v[122:123]
	s_nop 0
	v_pk_mul_f32 v[56:57], v[56:57], v[58:59]
	s_nop 0
	v_pk_mul_f32 v[58:59], v[56:57], v[56:57]
	s_nop 0
	v_add_f32_e32 v58, v58, v61
	v_cvt_pk_bf16_f32 v61, v56, v57
	v_lshl_add_u64 v[56:57], v[78:79], 0, v[64:65]
	global_store_dwordx2 v[56:57], v[60:61], off
	v_add_f32_e32 v121, v59, v58
	s_waitcnt vmcnt(8)
	v_lshlrev_b32_e32 v62, 16, v246
	s_waitcnt vmcnt(12)
	v_lshlrev_b32_e32 v122, 16, v238
	v_and_b32_e32 v123, 0xffff0000, v238
	v_and_b32_e32 v63, 0xffff0000, v246
	v_mul_f32_e32 v58, 0xbfb8aa3b, v122
	v_mul_f32_e32 v52, 0xbfb8aa3b, v123
	v_exp_f32_e32 v58, v58
	v_exp_f32_e32 v52, v52
	v_pk_fma_f32 v[48:49], v[252:253], v[62:63], v[48:49] op_sel_hi:[0,1,1]
	v_add_f32_e32 v58, 1.0, v58
	v_add_f32_e32 v52, 1.0, v52
	v_rcp_f32_e32 v124, v58
	v_rcp_f32_e32 v125, v52
	v_lshlrev_b32_e32 v58, 16, v239
	v_pk_mul_f32 v[52:53], v[124:125], v[122:123]
	s_nop 0
	v_pk_mul_f32 v[48:49], v[48:49], v[52:53]
	s_nop 0
	v_pk_mul_f32 v[52:53], v[48:49], v[48:49]
	v_cvt_pk_bf16_f32 v48, v48, v49
	v_mul_f32_e32 v49, 0xbfb8aa3b, v58
	v_exp_f32_e32 v49, v49
	v_add_f32_e32 v52, v52, v121
	v_add_f32_e32 v62, v53, v52
	v_lshlrev_b32_e32 v52, 16, v247
	v_and_b32_e32 v53, 0xffff0000, v247
	v_and_b32_e32 v59, 0xffff0000, v239
	v_add_f32_e32 v49, 1.0, v49
	v_rcp_f32_e32 v60, v49
	v_mul_f32_e32 v49, 0xbfb8aa3b, v59
	v_exp_f32_e32 v49, v49
	v_pk_fma_f32 v[50:51], v[252:253], v[52:53], v[50:51] op_sel_hi:[0,1,1]
	v_add_f32_e32 v49, 1.0, v49
	v_rcp_f32_e32 v61, v49
	s_nop 0
	v_pk_mul_f32 v[52:53], v[60:61], v[58:59]
	s_nop 0
	v_pk_mul_f32 v[50:51], v[50:51], v[52:53]
	s_nop 0
	v_pk_mul_f32 v[52:53], v[50:51], v[50:51]
	s_nop 0
	v_add_f32_e32 v49, v52, v62
	v_add_f32_e32 v60, v53, v49
	v_cvt_pk_bf16_f32 v49, v50, v51
	global_store_dwordx2 v[56:57], v[48:49], off offset:32
	s_waitcnt vmcnt(8)
	v_lshlrev_b32_e32 v52, 16, v248
	s_waitcnt vmcnt(12)
	v_lshlrev_b32_e32 v54, 16, v240
	v_and_b32_e32 v55, 0xffff0000, v240
	v_and_b32_e32 v53, 0xffff0000, v248
	v_mul_f32_e32 v48, 0xbfb8aa3b, v54
	v_mul_f32_e32 v44, 0xbfb8aa3b, v55
	v_exp_f32_e32 v48, v48
	v_exp_f32_e32 v44, v44
	v_pk_fma_f32 v[40:41], v[252:253], v[52:53], v[40:41] op_sel_hi:[0,1,1]
	v_add_f32_e32 v48, 1.0, v48
	v_add_f32_e32 v44, 1.0, v44
	v_rcp_f32_e32 v58, v48
	v_rcp_f32_e32 v59, v44
	v_lshlrev_b32_e32 v48, 16, v241
	v_pk_mul_f32 v[44:45], v[58:59], v[54:55]
	s_nop 0
	v_pk_mul_f32 v[40:41], v[40:41], v[44:45]
	s_nop 0
	v_pk_mul_f32 v[44:45], v[40:41], v[40:41]
	v_cvt_pk_bf16_f32 v40, v40, v41
	v_mul_f32_e32 v41, 0xbfb8aa3b, v48
	v_exp_f32_e32 v41, v41
	v_add_f32_e32 v44, v44, v60
	v_add_f32_e32 v52, v45, v44
	v_lshlrev_b32_e32 v44, 16, v249
	v_and_b32_e32 v45, 0xffff0000, v249
	v_and_b32_e32 v49, 0xffff0000, v241
	v_add_f32_e32 v41, 1.0, v41
	v_rcp_f32_e32 v50, v41
	v_mul_f32_e32 v41, 0xbfb8aa3b, v49
	v_exp_f32_e32 v41, v41
	v_pk_fma_f32 v[42:43], v[252:253], v[44:45], v[42:43] op_sel_hi:[0,1,1]
	v_add_f32_e32 v41, 1.0, v41
	v_rcp_f32_e32 v51, v41
	s_nop 0
	v_pk_mul_f32 v[44:45], v[50:51], v[48:49]
	s_nop 0
	v_pk_mul_f32 v[42:43], v[42:43], v[44:45]
	s_nop 0
	v_pk_mul_f32 v[44:45], v[42:43], v[42:43]
	s_nop 0
	v_add_f32_e32 v41, v44, v52
	v_add_f32_e32 v50, v45, v41
	v_cvt_pk_bf16_f32 v41, v42, v43
	global_store_dwordx2 v[56:57], v[40:41], off offset:64
	s_waitcnt vmcnt(8)
	v_lshlrev_b32_e32 v44, 16, v250
	s_waitcnt vmcnt(12)
	v_lshlrev_b32_e32 v46, 16, v242
	v_and_b32_e32 v47, 0xffff0000, v242
	v_and_b32_e32 v45, 0xffff0000, v250
	v_mul_f32_e32 v40, 0xbfb8aa3b, v46
	v_mul_f32_e32 v36, 0xbfb8aa3b, v47
	v_exp_f32_e32 v40, v40
	v_exp_f32_e32 v36, v36
	v_pk_fma_f32 v[32:33], v[252:253], v[44:45], v[32:33] op_sel_hi:[0,1,1]
	v_add_f32_e32 v40, 1.0, v40
	v_add_f32_e32 v36, 1.0, v36
	v_rcp_f32_e32 v48, v40
	v_rcp_f32_e32 v49, v36
	v_lshlrev_b32_e32 v40, 16, v243
	v_pk_mul_f32 v[36:37], v[48:49], v[46:47]
	s_nop 0
	v_pk_mul_f32 v[32:33], v[32:33], v[36:37]
	s_nop 0
	v_pk_mul_f32 v[36:37], v[32:33], v[32:33]
	v_cvt_pk_bf16_f32 v32, v32, v33
	v_mul_f32_e32 v33, 0xbfb8aa3b, v40
	v_exp_f32_e32 v33, v33
	v_add_f32_e32 v36, v36, v50
	v_add_f32_e32 v44, v37, v36
	v_lshlrev_b32_e32 v36, 16, v251
	v_and_b32_e32 v37, 0xffff0000, v251
	v_and_b32_e32 v41, 0xffff0000, v243
	v_add_f32_e32 v33, 1.0, v33
	v_rcp_f32_e32 v42, v33
	v_mul_f32_e32 v33, 0xbfb8aa3b, v41
	v_exp_f32_e32 v33, v33
	v_pk_fma_f32 v[34:35], v[252:253], v[36:37], v[34:35] op_sel_hi:[0,1,1]
	v_add_f32_e32 v33, 1.0, v33
	v_rcp_f32_e32 v43, v33
	s_nop 0
	v_pk_mul_f32 v[36:37], v[42:43], v[40:41]
	s_nop 0
	v_pk_mul_f32 v[34:35], v[34:35], v[36:37]
	s_nop 0
	v_pk_mul_f32 v[36:37], v[34:35], v[34:35]
	s_nop 0
	v_add_f32_e32 v33, v36, v44
	v_add_f32_e32 v121, v37, v33
	v_cvt_pk_bf16_f32 v33, v34, v35
	global_store_dwordx2 v[56:57], v[32:33], off offset:96
	s_barrier
	s_cbranch_scc0 .LBB0_651
	ds_bpermute_b32 v0, v109, v121
	v_lshl_or_b32 v4, v120, 9, v93
	v_readlane_b32 s0, v234, 23
	v_lshlrev_b32_e32 v64, 2, v4
	v_readlane_b32 s1, v234, 24
	s_waitcnt lgkmcnt(0)
	v_add_f32_e32 v5, v121, v0
	ds_bpermute_b32 v6, v110, v5
	v_lshl_add_u64 v[0:1], s[0:1], 0, v[64:65]
	s_mov_b32 s0, 0x800000
	v_add_u32_e32 v2, s73, v92
	v_ashrrev_i32_e32 v3, 31, v2
	s_waitcnt lgkmcnt(0)
	v_add_f32_e32 v5, v5, v6
	v_fmamk_f32 v5, v5, 0x3b000000, v118
	v_mul_f32_e32 v6, 0x4b800000, v5
	v_cmp_gt_f32_e32 vcc, s0, v5
	v_lshlrev_b64 v[2:3], 12, v[2:3]
	v_lshl_or_b32 v2, v4, 1, v2
	v_cndmask_b32_e32 v5, v5, v6, vcc
	v_rsq_f32_e32 v5, v5
	v_readlane_b32 s84, v234, 11
	v_readlane_b32 s86, v234, 13
	v_readlane_b32 s87, v234, 14
	v_mul_f32_e32 v4, 0x45800000, v5
	v_cndmask_b32_e32 v4, v5, v4, vcc
	v_lshl_add_u64 v[2:3], s[86:87], 0, v[2:3]
	v_mov_b32_e32 v5, v4
	s_mov_b64 s[94:95], 0
	v_readlane_b32 s85, v234, 12
